# phase 0 weight copies hand written: one compact routine for the 16 matrices, all of a wave's (at most 5) 64x32 items requested up front (dwordx4 loads), bf16 pairs transposed through a small LDS tile,
# speedup vs baseline: 1.0181x; 1.0181x over previous
.LBB0_17:
	v_writelane_b32 v251, s12, 3
	s_lshr_b32 s2, s85, 6
	s_lshl_b32 s95, s90, 3
	v_writelane_b32 v251, s13, 4
	s_add_i32 s88, s2, s95
	s_lshl_b32 s94, s92, 3
	v_writelane_b32 v251, s14, 5
	s_cmp_lt_i32 s86, 1
	v_writelane_b32 v251, s15, 6
	s_load_dwordx16 s[68:83], s[0:1], 0x40
	s_load_dwordx16 s[36:51], s[0:1], 0x80
	s_cselect_b64 s[6:7], -1, 0
	s_cmp_gt_i32 s86, 0
	v_writelane_b32 v251, s2, 7
	s_cselect_b64 s[2:3], -1, 0
	s_cmp_lt_i32 s87, 1
	s_cselect_b64 s[4:5], -1, 0
	s_or_b64 s[2:3], s[2:3], s[4:5]
	v_and_b32_e32 v152, 63, v153
	s_and_b64 vcc, exec, s[2:3]
	s_cbranch_vccnz .LBB0_1467
	v_readlane_b32 s18, v251, 7
	v_lshrrev_b32_e32 v212, 3, v152
	v_and_b32_e32 v213, 7, v152
	s_mul_i32 s18, s18, 0x1200
	v_mul_u32_u24_e32 v214, 0x240, v213
	v_lshl_add_u32 v214, v212, 2, v214
	v_add_u32_e32 v214, s18, v214
	v_mul_u32_u24_e32 v215, 0x90, v212
	v_lshl_add_u32 v215, v213, 4, v215
	v_add_u32_e32 v215, s18, v215
	v_mov_b32_e32 v231, 0
	v_lshlrev_b32_e32 v200, 4, v152
	s_mov_b32 s2, s88
	s_mov_b32 s3, 0
	s_mov_b32 s17, 0
	s_branch .Ltr_disp
.Ltr_disp:
	s_cmp_eq_u32 s3, 0
	s_cbranch_scc1 .Ltr_d0
	s_cmp_eq_u32 s3, 1
	s_cbranch_scc1 .Ltr_d1
	s_cmp_eq_u32 s3, 2
	s_cbranch_scc1 .Ltr_d2
	s_cmp_eq_u32 s3, 3
	s_cbranch_scc1 .Ltr_d3
	s_cmp_eq_u32 s3, 4
	s_cbranch_scc1 .Ltr_d4
	s_cmp_eq_u32 s3, 5
	s_cbranch_scc1 .Ltr_d5
	s_cmp_eq_u32 s3, 6
	s_cbranch_scc1 .Ltr_d6
	s_cmp_eq_u32 s3, 7
	s_cbranch_scc1 .Ltr_d7
	s_cmp_eq_u32 s3, 8
	s_cbranch_scc1 .Ltr_d8
	s_cmp_eq_u32 s3, 9
	s_cbranch_scc1 .Ltr_d9
	s_cmp_eq_u32 s3, 10
	s_cbranch_scc1 .Ltr_d10
	s_cmp_eq_u32 s3, 11
	s_cbranch_scc1 .Ltr_d11
	s_cmp_eq_u32 s3, 12
	s_cbranch_scc1 .Ltr_d12
	s_cmp_eq_u32 s3, 13
	s_cbranch_scc1 .Ltr_d13
	s_cmp_eq_u32 s3, 14
	s_cbranch_scc1 .Ltr_d14
	s_cmp_eq_u32 s3, 15
	s_cbranch_scc1 .Ltr_d15
	s_branch .Ltr_d0
.Ltr_d0:
	s_load_dwordx2 s[4:5], s[0:1], 0x18
	s_movk_i32 s8, 0x1418
	s_movk_i32 s9, 0x400
	s_mov_b32 s10, 0x100000
	s_mov_b32 s11, 1
	s_movk_i32 s12, 0xa1
	s_mov_b32 s13, 0x1970e50
	s_movk_i32 s14, 0x0
	s_movk_i32 s15, 0xa10
	s_mov_b32 s16, 0
	s_waitcnt lgkmcnt(0)
	s_mov_b64 s[32:33], s[4:5]
	s_branch .Ltr_ret
.Ltr_d1:
	s_load_dwordx2 s[4:5], s[0:1], 0xf0
	s_load_dwordx2 s[32:33], s[0:1], 0xe8
	s_movk_i32 s8, 0x1600
	s_movk_i32 s9, 0x400
	s_mov_b32 s10, 0x1800000
	s_mov_b32 s11, 2
	s_movk_i32 s12, 0xb0
	s_mov_b32 s13, 0x1745d18
	s_movk_i32 s14, 0xa10
	s_movk_i32 s15, 0x1510
	s_mov_b32 s16, 1
	s_waitcnt lgkmcnt(0)
	s_branch .Ltr_ret
.Ltr_d2:
	s_load_dwordx2 s[4:5], s[0:1], 0xf8
	s_movk_i32 s8, 0x400
	s_movk_i32 s9, 0xb00
	s_mov_b32 s10, 0x2300000
	s_mov_b32 s11, 0
	s_movk_i32 s12, 0x20
	s_mov_b32 s13, 0x8000000
	s_movk_i32 s14, 0x1510
	s_movk_i32 s15, 0x1a90
	s_mov_b32 s16, 0
	s_waitcnt lgkmcnt(0)
	s_mov_b64 s[32:33], s[4:5]
	s_branch .Ltr_ret
.Ltr_d3:
	s_load_dwordx2 s[4:5], s[0:1], 0xd8
	s_movk_i32 s8, 0x800
	s_movk_i32 s9, 0x400
	s_mov_b32 s10, 0x1200000
	s_mov_b32 s11, 0
	s_movk_i32 s12, 0x40
	s_mov_b32 s13, 0x4000000
	s_movk_i32 s14, 0x1a90
	s_movk_i32 s15, 0x1e90
	s_mov_b32 s16, 0
	s_waitcnt lgkmcnt(0)
	s_mov_b64 s[32:33], s[4:5]
	s_branch .Ltr_ret
.Ltr_d4:
	s_load_dwordx2 s[4:5], s[0:1], 0xb8
	s_movk_i32 s8, 0x400
	s_movk_i32 s9, 0x400
	s_mov_b32 s10, 0xe00000
	s_mov_b32 s11, 0
	s_movk_i32 s12, 0x20
	s_mov_b32 s13, 0x8000000
	s_movk_i32 s14, 0x1e90
	s_movk_i32 s15, 0x2090
	s_mov_b32 s16, 0
	s_waitcnt lgkmcnt(0)
	s_mov_b64 s[32:33], s[4:5]
	s_branch .Ltr_ret
.Ltr_d5:
	s_load_dwordx2 s[4:5], s[0:1], 0xd0
	s_load_dwordx2 s[32:33], s[0:1], 0xc0
	s_movk_i32 s8, 0x400
	s_movk_i32 s9, 0x400
	s_mov_b32 s10, 0x1000000
	s_mov_b32 s11, 0
	s_movk_i32 s12, 0x20
	s_mov_b32 s13, 0x8000000
	s_movk_i32 s14, 0x2090
	s_movk_i32 s15, 0x2290
	s_mov_b32 s16, 1
	s_waitcnt lgkmcnt(0)
	s_branch .Ltr_ret
.Ltr_d6:
	s_load_dwordx2 s[4:5], s[0:1], 0xe0
	s_movk_i32 s8, 0x400
	s_movk_i32 s9, 0x400
	s_mov_b32 s10, 0x1600000
	s_mov_b32 s11, 0
	s_movk_i32 s12, 0x20
	s_mov_b32 s13, 0x8000000
	s_movk_i32 s14, 0x2290
	s_movk_i32 s15, 0x2490
	s_mov_b32 s16, 0
	s_waitcnt lgkmcnt(0)
	s_mov_b64 s[32:33], s[4:5]
	s_branch .Ltr_ret
.Ltr_d7:
	s_load_dwordx2 s[4:5], s[0:1], 0xa8
	s_movk_i32 s8, 0x400
	s_movk_i32 s9, 0x200
	s_mov_b32 s10, 0xc00000
	s_mov_b32 s11, 0
	s_movk_i32 s12, 0x20
	s_mov_b32 s13, 0x8000000
	s_movk_i32 s14, 0x2490
	s_movk_i32 s15, 0x2590
	s_mov_b32 s16, 0
	s_waitcnt lgkmcnt(0)
	s_mov_b64 s[32:33], s[4:5]
	s_branch .Ltr_ret
.Ltr_d8:
	s_load_dwordx2 s[4:5], s[0:1], 0xb0
	s_movk_i32 s8, 0x400
	s_movk_i32 s9, 0x200
	s_mov_b32 s10, 0xd00000
	s_mov_b32 s11, 0
	s_movk_i32 s12, 0x20
	s_mov_b32 s13, 0x8000000
	s_movk_i32 s14, 0x2590
	s_movk_i32 s15, 0x2690
	s_mov_b32 s16, 0
	s_waitcnt lgkmcnt(0)
	s_mov_b64 s[32:33], s[4:5]
	s_branch .Ltr_ret
.Ltr_d9:
	s_load_dwordx2 s[4:5], s[0:1], 0x28
	s_movk_i32 s8, 0x200
	s_movk_i32 s9, 0x40
	s_mov_b32 s10, 0x2900000
	s_mov_b32 s11, 0
	s_movk_i32 s12, 0x10
	s_mov_b32 s13, 0x10000000
	s_movk_i32 s14, 0x2690
	s_movk_i32 s15, 0x26a0
	s_mov_b32 s16, 0
	s_waitcnt lgkmcnt(0)
	s_mov_b64 s[32:33], s[4:5]
	s_branch .Ltr_ret
.Ltr_d10:
	s_load_dwordx2 s[4:5], s[0:1], 0x38
	s_movk_i32 s8, 0x200
	s_movk_i32 s9, 0x40
	s_mov_b32 s10, 0x2910000
	s_mov_b32 s11, 0
	s_movk_i32 s12, 0x10
	s_mov_b32 s13, 0x10000000
	s_movk_i32 s14, 0x26a0
	s_movk_i32 s15, 0x26b0
	s_mov_b32 s16, 0
	s_waitcnt lgkmcnt(0)
	s_mov_b64 s[32:33], s[4:5]
	s_branch .Ltr_ret
.Ltr_d11:
	s_load_dwordx2 s[4:5], s[0:1], 0x48
	s_movk_i32 s8, 0x200
	s_movk_i32 s9, 0x80
	s_mov_b32 s10, 0x2920000
	s_mov_b32 s11, 0
	s_movk_i32 s12, 0x10
	s_mov_b32 s13, 0x10000000
	s_movk_i32 s14, 0x26b0
	s_movk_i32 s15, 0x26d0
	s_mov_b32 s16, 0
	s_waitcnt lgkmcnt(0)
	s_mov_b64 s[32:33], s[4:5]
	s_branch .Ltr_ret
.Ltr_d12:
	s_load_dwordx2 s[4:5], s[0:1], 0x88
	s_movk_i32 s8, 0x80
	s_movk_i32 s9, 0x800
	s_mov_b32 s10, 0x2a00000
	s_mov_b32 s11, 0
	s_movk_i32 s12, 0x4
	s_mov_b32 s13, 0x40000000
	s_movk_i32 s14, 0x26d0
	s_movk_i32 s15, 0x2750
	s_mov_b32 s16, 0
	s_waitcnt lgkmcnt(0)
	s_mov_b64 s[32:33], s[4:5]
	s_branch .Ltr_ret
.Ltr_d13:
	s_load_dwordx2 s[4:5], s[0:1], 0x98
	s_movk_i32 s8, 0x80
	s_movk_i32 s9, 0x800
	s_mov_b32 s10, 0x2a80000
	s_mov_b32 s11, 0
	s_movk_i32 s12, 0x4
	s_mov_b32 s13, 0x40000000
	s_movk_i32 s14, 0x2750
	s_movk_i32 s15, 0x27d0
	s_mov_b32 s16, 0
	s_waitcnt lgkmcnt(0)
	s_mov_b64 s[32:33], s[4:5]
	s_branch .Ltr_ret
.Ltr_d14:
	s_load_dwordx2 s[4:5], s[0:1], 0x90
	s_movk_i32 s8, 0x40
	s_movk_i32 s9, 0x80
	s_mov_b32 s10, 0x2b00000
	s_mov_b32 s11, 0
	s_movk_i32 s12, 0x2
	s_mov_b32 s13, 0x80000000
	s_movk_i32 s14, 0x27d0
	s_movk_i32 s15, 0x27d4
	s_mov_b32 s16, 0
	s_waitcnt lgkmcnt(0)
	s_mov_b64 s[32:33], s[4:5]
	s_branch .Ltr_ret
.Ltr_d15:
	s_load_dwordx2 s[4:5], s[0:1], 0xa0
	s_movk_i32 s8, 0x40
	s_movk_i32 s9, 0x80
	s_mov_b32 s10, 0x2b04000
	s_mov_b32 s11, 0
	s_movk_i32 s12, 0x2
	s_mov_b32 s13, 0x80000000
	s_movk_i32 s14, 0x27d4
	s_movk_i32 s15, 0x27d8
	s_mov_b32 s16, 0
	s_waitcnt lgkmcnt(0)
	s_mov_b64 s[32:33], s[4:5]
	s_branch .Ltr_ret
.Ltr_ret:
	s_cmp_eq_u32 s17, 0
	s_cbranch_scc1 .Ltr_w0
	s_cmp_eq_u32 s17, 1
	s_cbranch_scc1 .Ltr_w1
	s_cmp_eq_u32 s17, 2
	s_cbranch_scc1 .Ltr_w2
	s_cmp_eq_u32 s17, 3
	s_cbranch_scc1 .Ltr_w3
	s_cmp_eq_u32 s17, 4
	s_cbranch_scc1 .Ltr_w4
	s_branch .Ltr_w0
.Ltr_w0:
	s_cmp_lt_u32 s2, 0x27d8
	s_cbranch_scc0 .Ltr_none0
	s_cmp_lt_u32 s2, s15
	s_cbranch_scc1 .Ltr_have0
	s_add_i32 s3, s3, 1
	s_mov_b32 s17, 0
	s_branch .Ltr_disp
.Ltr_have0:
	s_sub_i32 s18, s2, s14
	s_mul_hi_u32 s19, s18, s13
	s_mul_i32 s20, s19, s12
	s_sub_i32 s20, s18, s20
	s_lshl_b32 s19, s19, 6
	s_lshl_b32 s20, s20, 5
	s_add_u32 s21, s96, s10
	s_addc_u32 s22, s97, 0
	v_writelane_b32 v230, s21, 0
	v_writelane_b32 v230, s22, 1
	v_writelane_b32 v230, s9, 2
	v_writelane_b32 v230, s11, 3
	v_writelane_b32 v230, s8, 4
	v_writelane_b32 v230, s20, 5
	v_writelane_b32 v230, s19, 6
	v_writelane_b32 v230, s16, 7
	s_mov_b32 s23, 1
	v_writelane_b32 v230, s23, 40
	v_lshl_add_u32 v225, v213, 2, s20
	v_cmp_gt_u32_e32 vcc, s8, v225
	v_lshl_add_u32 v224, v212, 1, s19
	s_nop 1
	v_cndmask_b32_e32 v225, 0, v225, vcc
	v_mul_lo_u32 v216, v224, s8
	v_add_lshl_u32 v216, v216, v225, 2
	s_lshl_b32 s21, s8, 2
	s_lshl_b32 s22, s8, 6
	v_add_u32_e32 v217, s21, v216
	v_add_u32_e32 v218, s22, v216
	v_add_u32_e32 v219, s21, v218
	v_add_u32_e32 v220, s22, v218
	v_add_u32_e32 v221, s21, v220
	v_add_u32_e32 v222, s22, v220
	v_add_u32_e32 v223, s21, v222
	v_lshlrev_b32_e32 v224, 2, v224
	global_load_dwordx4 v[0:3], v216, s[4:5]
	global_load_dwordx4 v[4:7], v217, s[4:5]
	global_load_dwordx4 v[8:11], v218, s[4:5]
	global_load_dwordx4 v[12:15], v219, s[4:5]
	global_load_dwordx4 v[16:19], v220, s[4:5]
	global_load_dwordx4 v[20:23], v221, s[4:5]
	global_load_dwordx4 v[24:27], v222, s[4:5]
	global_load_dwordx4 v[28:31], v223, s[4:5]
	global_load_dwordx2 v[128:129], v224, s[32:33] offset:0
	global_load_dwordx2 v[130:131], v224, s[32:33] offset:64
	global_load_dwordx2 v[132:133], v224, s[32:33] offset:128
	global_load_dwordx2 v[134:135], v224, s[32:33] offset:192
	s_add_i32 s2, s2, s94
	s_branch .Ltr_next0
.Ltr_none0:
	s_mov_b32 s23, 0
	v_writelane_b32 v230, s23, 40
	global_load_dwordx4 v[0:3], v200, s[96:97]
	global_load_dwordx4 v[4:7], v200, s[96:97]
	global_load_dwordx4 v[8:11], v200, s[96:97]
	global_load_dwordx4 v[12:15], v200, s[96:97]
	global_load_dwordx4 v[16:19], v200, s[96:97]
	global_load_dwordx4 v[20:23], v200, s[96:97]
	global_load_dwordx4 v[24:27], v200, s[96:97]
	global_load_dwordx4 v[28:31], v200, s[96:97]
	global_load_dwordx2 v[128:129], v200, s[96:97]
	global_load_dwordx2 v[130:131], v200, s[96:97]
	global_load_dwordx2 v[132:133], v200, s[96:97]
	global_load_dwordx2 v[134:135], v200, s[96:97]
.Ltr_next0:
.Ltr_w1:
	s_cmp_lt_u32 s2, 0x27d8
	s_cbranch_scc0 .Ltr_none1
	s_cmp_lt_u32 s2, s15
	s_cbranch_scc1 .Ltr_have1
	s_add_i32 s3, s3, 1
	s_mov_b32 s17, 1
	s_branch .Ltr_disp
.Ltr_have1:
	s_sub_i32 s18, s2, s14
	s_mul_hi_u32 s19, s18, s13
	s_mul_i32 s20, s19, s12
	s_sub_i32 s20, s18, s20
	s_lshl_b32 s19, s19, 6
	s_lshl_b32 s20, s20, 5
	s_add_u32 s21, s96, s10
	s_addc_u32 s22, s97, 0
	v_writelane_b32 v230, s21, 8
	v_writelane_b32 v230, s22, 9
	v_writelane_b32 v230, s9, 10
	v_writelane_b32 v230, s11, 11
	v_writelane_b32 v230, s8, 12
	v_writelane_b32 v230, s20, 13
	v_writelane_b32 v230, s19, 14
	v_writelane_b32 v230, s16, 15
	s_mov_b32 s23, 1
	v_writelane_b32 v230, s23, 41
	v_lshl_add_u32 v225, v213, 2, s20
	v_cmp_gt_u32_e32 vcc, s8, v225
	v_lshl_add_u32 v224, v212, 1, s19
	s_nop 1
	v_cndmask_b32_e32 v225, 0, v225, vcc
	v_mul_lo_u32 v216, v224, s8
	v_add_lshl_u32 v216, v216, v225, 2
	s_lshl_b32 s21, s8, 2
	s_lshl_b32 s22, s8, 6
	v_add_u32_e32 v217, s21, v216
	v_add_u32_e32 v218, s22, v216
	v_add_u32_e32 v219, s21, v218
	v_add_u32_e32 v220, s22, v218
	v_add_u32_e32 v221, s21, v220
	v_add_u32_e32 v222, s22, v220
	v_add_u32_e32 v223, s21, v222
	v_lshlrev_b32_e32 v224, 2, v224
	global_load_dwordx4 v[32:35], v216, s[4:5]
	global_load_dwordx4 v[36:39], v217, s[4:5]
	global_load_dwordx4 v[40:43], v218, s[4:5]
	global_load_dwordx4 v[44:47], v219, s[4:5]
	global_load_dwordx4 v[48:51], v220, s[4:5]
	global_load_dwordx4 v[52:55], v221, s[4:5]
	global_load_dwordx4 v[56:59], v222, s[4:5]
	global_load_dwordx4 v[60:63], v223, s[4:5]
	global_load_dwordx2 v[136:137], v224, s[32:33] offset:0
	global_load_dwordx2 v[138:139], v224, s[32:33] offset:64
	global_load_dwordx2 v[140:141], v224, s[32:33] offset:128
	global_load_dwordx2 v[142:143], v224, s[32:33] offset:192
	s_add_i32 s2, s2, s94
	s_branch .Ltr_next1
.Ltr_none1:
	s_mov_b32 s23, 0
	v_writelane_b32 v230, s23, 41
	global_load_dwordx4 v[32:35], v200, s[96:97]
	global_load_dwordx4 v[36:39], v200, s[96:97]
	global_load_dwordx4 v[40:43], v200, s[96:97]
	global_load_dwordx4 v[44:47], v200, s[96:97]
	global_load_dwordx4 v[48:51], v200, s[96:97]
	global_load_dwordx4 v[52:55], v200, s[96:97]
	global_load_dwordx4 v[56:59], v200, s[96:97]
	global_load_dwordx4 v[60:63], v200, s[96:97]
	global_load_dwordx2 v[136:137], v200, s[96:97]
	global_load_dwordx2 v[138:139], v200, s[96:97]
	global_load_dwordx2 v[140:141], v200, s[96:97]
	global_load_dwordx2 v[142:143], v200, s[96:97]
.Ltr_next1:
.Ltr_w2:
	s_cmp_lt_u32 s2, 0x27d8
	s_cbranch_scc0 .Ltr_none2
	s_cmp_lt_u32 s2, s15
	s_cbranch_scc1 .Ltr_have2
	s_add_i32 s3, s3, 1
	s_mov_b32 s17, 2
	s_branch .Ltr_disp
.Ltr_have2:
	s_sub_i32 s18, s2, s14
	s_mul_hi_u32 s19, s18, s13
	s_mul_i32 s20, s19, s12
	s_sub_i32 s20, s18, s20
	s_lshl_b32 s19, s19, 6
	s_lshl_b32 s20, s20, 5
	s_add_u32 s21, s96, s10
	s_addc_u32 s22, s97, 0
	v_writelane_b32 v230, s21, 16
	v_writelane_b32 v230, s22, 17
	v_writelane_b32 v230, s9, 18
	v_writelane_b32 v230, s11, 19
	v_writelane_b32 v230, s8, 20
	v_writelane_b32 v230, s20, 21
	v_writelane_b32 v230, s19, 22
	v_writelane_b32 v230, s16, 23
	s_mov_b32 s23, 1
	v_writelane_b32 v230, s23, 42
	v_lshl_add_u32 v225, v213, 2, s20
	v_cmp_gt_u32_e32 vcc, s8, v225
	v_lshl_add_u32 v224, v212, 1, s19
	s_nop 1
	v_cndmask_b32_e32 v225, 0, v225, vcc
	v_mul_lo_u32 v216, v224, s8
	v_add_lshl_u32 v216, v216, v225, 2
	s_lshl_b32 s21, s8, 2
	s_lshl_b32 s22, s8, 6
	v_add_u32_e32 v217, s21, v216
	v_add_u32_e32 v218, s22, v216
	v_add_u32_e32 v219, s21, v218
	v_add_u32_e32 v220, s22, v218
	v_add_u32_e32 v221, s21, v220
	v_add_u32_e32 v222, s22, v220
	v_add_u32_e32 v223, s21, v222
	v_lshlrev_b32_e32 v224, 2, v224
	global_load_dwordx4 v[64:67], v216, s[4:5]
	global_load_dwordx4 v[68:71], v217, s[4:5]
	global_load_dwordx4 v[72:75], v218, s[4:5]
	global_load_dwordx4 v[76:79], v219, s[4:5]
	global_load_dwordx4 v[80:83], v220, s[4:5]
	global_load_dwordx4 v[84:87], v221, s[4:5]
	global_load_dwordx4 v[88:91], v222, s[4:5]
	global_load_dwordx4 v[92:95], v223, s[4:5]
	global_load_dwordx2 v[144:145], v224, s[32:33] offset:0
	global_load_dwordx2 v[146:147], v224, s[32:33] offset:64
	global_load_dwordx2 v[148:149], v224, s[32:33] offset:128
	global_load_dwordx2 v[150:151], v224, s[32:33] offset:192
	s_add_i32 s2, s2, s94
	s_branch .Ltr_next2
.Ltr_none2:
	s_mov_b32 s23, 0
	v_writelane_b32 v230, s23, 42
	global_load_dwordx4 v[64:67], v200, s[96:97]
	global_load_dwordx4 v[68:71], v200, s[96:97]
	global_load_dwordx4 v[72:75], v200, s[96:97]
	global_load_dwordx4 v[76:79], v200, s[96:97]
	global_load_dwordx4 v[80:83], v200, s[96:97]
	global_load_dwordx4 v[84:87], v200, s[96:97]
	global_load_dwordx4 v[88:91], v200, s[96:97]
	global_load_dwordx4 v[92:95], v200, s[96:97]
	global_load_dwordx2 v[144:145], v200, s[96:97]
	global_load_dwordx2 v[146:147], v200, s[96:97]
	global_load_dwordx2 v[148:149], v200, s[96:97]
	global_load_dwordx2 v[150:151], v200, s[96:97]
.Ltr_next2:
.Ltr_w3:
	s_cmp_lt_u32 s2, 0x27d8
	s_cbranch_scc0 .Ltr_none3
	s_cmp_lt_u32 s2, s15
	s_cbranch_scc1 .Ltr_have3
	s_add_i32 s3, s3, 1
	s_mov_b32 s17, 3
	s_branch .Ltr_disp
.Ltr_have3:
	s_sub_i32 s18, s2, s14
	s_mul_hi_u32 s19, s18, s13
	s_mul_i32 s20, s19, s12
	s_sub_i32 s20, s18, s20
	s_lshl_b32 s19, s19, 6
	s_lshl_b32 s20, s20, 5
	s_add_u32 s21, s96, s10
	s_addc_u32 s22, s97, 0
	v_writelane_b32 v230, s21, 24
	v_writelane_b32 v230, s22, 25
	v_writelane_b32 v230, s9, 26
	v_writelane_b32 v230, s11, 27
	v_writelane_b32 v230, s8, 28
	v_writelane_b32 v230, s20, 29
	v_writelane_b32 v230, s19, 30
	v_writelane_b32 v230, s16, 31
	s_mov_b32 s23, 1
	v_writelane_b32 v230, s23, 43
	v_lshl_add_u32 v225, v213, 2, s20
	v_cmp_gt_u32_e32 vcc, s8, v225
	v_lshl_add_u32 v224, v212, 1, s19
	s_nop 1
	v_cndmask_b32_e32 v225, 0, v225, vcc
	v_mul_lo_u32 v216, v224, s8
	v_add_lshl_u32 v216, v216, v225, 2
	s_lshl_b32 s21, s8, 2
	s_lshl_b32 s22, s8, 6
	v_add_u32_e32 v217, s21, v216
	v_add_u32_e32 v218, s22, v216
	v_add_u32_e32 v219, s21, v218
	v_add_u32_e32 v220, s22, v218
	v_add_u32_e32 v221, s21, v220
	v_add_u32_e32 v222, s22, v220
	v_add_u32_e32 v223, s21, v222
	v_lshlrev_b32_e32 v224, 2, v224
	global_load_dwordx4 v[96:99], v216, s[4:5]
	global_load_dwordx4 v[100:103], v217, s[4:5]
	global_load_dwordx4 v[104:107], v218, s[4:5]
	global_load_dwordx4 v[108:111], v219, s[4:5]
	global_load_dwordx4 v[112:115], v220, s[4:5]
	global_load_dwordx4 v[116:119], v221, s[4:5]
	global_load_dwordx4 v[120:123], v222, s[4:5]
	global_load_dwordx4 v[124:127], v223, s[4:5]
	global_load_dwordx2 v[192:193], v224, s[32:33] offset:0
	global_load_dwordx2 v[194:195], v224, s[32:33] offset:64
	global_load_dwordx2 v[196:197], v224, s[32:33] offset:128
	global_load_dwordx2 v[198:199], v224, s[32:33] offset:192
	s_add_i32 s2, s2, s94
	s_branch .Ltr_next3
.Ltr_none3:
	s_mov_b32 s23, 0
	v_writelane_b32 v230, s23, 43
	global_load_dwordx4 v[96:99], v200, s[96:97]
	global_load_dwordx4 v[100:103], v200, s[96:97]
	global_load_dwordx4 v[104:107], v200, s[96:97]
	global_load_dwordx4 v[108:111], v200, s[96:97]
	global_load_dwordx4 v[112:115], v200, s[96:97]
	global_load_dwordx4 v[116:119], v200, s[96:97]
	global_load_dwordx4 v[120:123], v200, s[96:97]
	global_load_dwordx4 v[124:127], v200, s[96:97]
	global_load_dwordx2 v[192:193], v200, s[96:97]
	global_load_dwordx2 v[194:195], v200, s[96:97]
	global_load_dwordx2 v[196:197], v200, s[96:97]
	global_load_dwordx2 v[198:199], v200, s[96:97]
.Ltr_next3:
.Ltr_w4:
	s_cmp_lt_u32 s2, 0x27d8
	s_cbranch_scc0 .Ltr_none4
	s_cmp_lt_u32 s2, s15
	s_cbranch_scc1 .Ltr_have4
	s_add_i32 s3, s3, 1
	s_mov_b32 s17, 4
	s_branch .Ltr_disp
.Ltr_have4:
	s_sub_i32 s18, s2, s14
	s_mul_hi_u32 s19, s18, s13
	s_mul_i32 s20, s19, s12
	s_sub_i32 s20, s18, s20
	s_lshl_b32 s19, s19, 6
	s_lshl_b32 s20, s20, 5
	s_add_u32 s21, s96, s10
	s_addc_u32 s22, s97, 0
	v_writelane_b32 v230, s21, 32
	v_writelane_b32 v230, s22, 33
	v_writelane_b32 v230, s9, 34
	v_writelane_b32 v230, s11, 35
	v_writelane_b32 v230, s8, 36
	v_writelane_b32 v230, s20, 37
	v_writelane_b32 v230, s19, 38
	v_writelane_b32 v230, s16, 39
	s_mov_b32 s23, 1
	v_writelane_b32 v230, s23, 44
	v_lshl_add_u32 v225, v213, 2, s20
	v_cmp_gt_u32_e32 vcc, s8, v225
	v_lshl_add_u32 v224, v212, 1, s19
	s_nop 1
	v_cndmask_b32_e32 v225, 0, v225, vcc
	v_mul_lo_u32 v216, v224, s8
	v_add_lshl_u32 v216, v216, v225, 2
	s_lshl_b32 s21, s8, 2
	s_lshl_b32 s22, s8, 6
	v_add_u32_e32 v217, s21, v216
	v_add_u32_e32 v218, s22, v216
	v_add_u32_e32 v219, s21, v218
	v_add_u32_e32 v220, s22, v218
	v_add_u32_e32 v221, s21, v220
	v_add_u32_e32 v222, s22, v220
	v_add_u32_e32 v223, s21, v222
	v_lshlrev_b32_e32 v224, 2, v224
	global_load_dwordx4 v[160:163], v216, s[4:5]
	global_load_dwordx4 v[164:167], v217, s[4:5]
	global_load_dwordx4 v[168:171], v218, s[4:5]
	global_load_dwordx4 v[172:175], v219, s[4:5]
	global_load_dwordx4 v[176:179], v220, s[4:5]
	global_load_dwordx4 v[180:183], v221, s[4:5]
	global_load_dwordx4 v[184:187], v222, s[4:5]
	global_load_dwordx4 v[188:191], v223, s[4:5]
	global_load_dwordx2 v[204:205], v224, s[32:33] offset:0
	global_load_dwordx2 v[206:207], v224, s[32:33] offset:64
	global_load_dwordx2 v[208:209], v224, s[32:33] offset:128
	global_load_dwordx2 v[210:211], v224, s[32:33] offset:192
	s_add_i32 s2, s2, s94
	s_branch .Ltr_next4
.Ltr_none4:
	s_mov_b32 s23, 0
	v_writelane_b32 v230, s23, 44
	global_load_dwordx4 v[160:163], v200, s[96:97]
	global_load_dwordx4 v[164:167], v200, s[96:97]
	global_load_dwordx4 v[168:171], v200, s[96:97]
	global_load_dwordx4 v[172:175], v200, s[96:97]
	global_load_dwordx4 v[176:179], v200, s[96:97]
	global_load_dwordx4 v[180:183], v200, s[96:97]
	global_load_dwordx4 v[184:187], v200, s[96:97]
	global_load_dwordx4 v[188:191], v200, s[96:97]
	global_load_dwordx2 v[204:205], v200, s[96:97]
	global_load_dwordx2 v[206:207], v200, s[96:97]
	global_load_dwordx2 v[208:209], v200, s[96:97]
	global_load_dwordx2 v[210:211], v200, s[96:97]
.Ltr_next4:
	v_readlane_b32 s23, v230, 40
	v_readlane_b32 s24, v230, 0
	v_readlane_b32 s25, v230, 1
	v_readlane_b32 s26, v230, 2
	v_readlane_b32 s27, v230, 3
	v_readlane_b32 s28, v230, 4
	v_readlane_b32 s29, v230, 5
	v_readlane_b32 s30, v230, 6
	v_readlane_b32 s31, v230, 7
	s_cmp_eq_u32 s23, 0
	s_cbranch_scc1 .Ltr_done
	s_waitcnt vmcnt(48)
	s_cmp_eq_u32 s31, 0
	s_cbranch_scc1 .Ltr_ns0
	v_mul_f32_e32 v0, v0, v128
	v_mul_f32_e32 v4, v4, v129
	v_mul_f32_e32 v1, v1, v128
	v_mul_f32_e32 v5, v5, v129
	v_mul_f32_e32 v2, v2, v128
	v_mul_f32_e32 v6, v6, v129
	v_mul_f32_e32 v3, v3, v128
	v_mul_f32_e32 v7, v7, v129
	v_mul_f32_e32 v8, v8, v130
	v_mul_f32_e32 v12, v12, v131
	v_mul_f32_e32 v9, v9, v130
	v_mul_f32_e32 v13, v13, v131
	v_mul_f32_e32 v10, v10, v130
	v_mul_f32_e32 v14, v14, v131
	v_mul_f32_e32 v11, v11, v130
	v_mul_f32_e32 v15, v15, v131
	v_mul_f32_e32 v16, v16, v132
	v_mul_f32_e32 v20, v20, v133
	v_mul_f32_e32 v17, v17, v132
	v_mul_f32_e32 v21, v21, v133
	v_mul_f32_e32 v18, v18, v132
	v_mul_f32_e32 v22, v22, v133
	v_mul_f32_e32 v19, v19, v132
	v_mul_f32_e32 v23, v23, v133
	v_mul_f32_e32 v24, v24, v134
	v_mul_f32_e32 v28, v28, v135
	v_mul_f32_e32 v25, v25, v134
	v_mul_f32_e32 v29, v29, v135
	v_mul_f32_e32 v26, v26, v134
	v_mul_f32_e32 v30, v30, v135
	v_mul_f32_e32 v27, v27, v134
	v_mul_f32_e32 v31, v31, v135
.Ltr_ns0:
	v_cvt_pk_bf16_f32 v226, v0, v4
	v_cvt_pk_bf16_f32 v227, v1, v5
	v_cvt_pk_bf16_f32 v228, v2, v6
	v_cvt_pk_bf16_f32 v229, v3, v7
	ds_write_b32 v214, v226 offset:0
	ds_write_b32 v214, v227 offset:144
	ds_write_b32 v214, v228 offset:288
	ds_write_b32 v214, v229 offset:432
	v_cvt_pk_bf16_f32 v226, v8, v12
	v_cvt_pk_bf16_f32 v227, v9, v13
	v_cvt_pk_bf16_f32 v228, v10, v14
	v_cvt_pk_bf16_f32 v229, v11, v15
	ds_write_b32 v214, v226 offset:32
	ds_write_b32 v214, v227 offset:176
	ds_write_b32 v214, v228 offset:320
	ds_write_b32 v214, v229 offset:464
	v_cvt_pk_bf16_f32 v226, v16, v20
	v_cvt_pk_bf16_f32 v227, v17, v21
	v_cvt_pk_bf16_f32 v228, v18, v22
	v_cvt_pk_bf16_f32 v229, v19, v23
	ds_write_b32 v214, v226 offset:64
	ds_write_b32 v214, v227 offset:208
	ds_write_b32 v214, v228 offset:352
	ds_write_b32 v214, v229 offset:496
	v_cvt_pk_bf16_f32 v226, v24, v28
	v_cvt_pk_bf16_f32 v227, v25, v29
	v_cvt_pk_bf16_f32 v228, v26, v30
	v_cvt_pk_bf16_f32 v229, v27, v31
	ds_write_b32 v214, v226 offset:96
	ds_write_b32 v214, v227 offset:240
	ds_write_b32 v214, v228 offset:384
	ds_write_b32 v214, v229 offset:528
	s_waitcnt lgkmcnt(0)
	ds_read_b128 v[232:235], v215 offset:0
	ds_read_b128 v[236:239], v215 offset:1152
	ds_read_b128 v[240:243], v215 offset:2304
	ds_read_b128 v[244:247], v215 offset:3456
	v_lshl_add_u32 v250, v213, 3, s30
	s_waitcnt lgkmcnt(0)
	v_add_u32_e32 v248, 0, v212
	v_add_u32_e32 v248, s29, v248
	v_cmp_gt_u32_e32 vcc, s28, v248
	s_and_saveexec_b64 s[18:19], vcc
	s_cmp_eq_u32 s27, 0
	s_cbranch_scc1 .Ltr_m0_0_0
	s_cmp_eq_u32 s27, 2
	s_cbranch_scc1 .Ltr_m2_0_0
	v_add_u32_e32 v249, 0x800, v248
	v_cmp_gt_u32_e32 vcc, 0xc18, v248
	v_subrev_u32_e32 v226, 24, v248
	s_nop 1
	v_cndmask_b32_e32 v249, v226, v249, vcc
	v_cmp_gt_u32_e32 vcc, 0xc00, v248
	s_nop 1
	v_cndmask_b32_e32 v248, v249, v248, vcc
	s_branch .Ltr_m0_0_0
.Ltr_m2_0_0:
	v_cmp_gt_u32_e32 vcc, 0xb00, v248
	v_subrev_u32_e32 v249, 0xb00, v248
	v_mov_b32_e32 v227, 0x80
	s_nop 1
	v_cndmask_b32_e32 v249, v249, v248, vcc
	v_cndmask_b32_e32 v226, v227, v231, vcc
	v_lshrrev_b32_e32 v248, 7, v249
	v_and_b32_e32 v249, 0x7f, v249
	v_lshl_add_u32 v248, v248, 8, v249
	v_add_u32_e32 v248, v248, v226
.Ltr_m0_0_0:
	v_mul_lo_u32 v248, v248, s26
	v_add_lshl_u32 v248, v248, v250, 1
	global_store_dwordx4 v248, v[232:235], s[24:25]
	s_or_b64 exec, exec, s[18:19]
	v_add_u32_e32 v248, 8, v212
	v_add_u32_e32 v248, s29, v248
	v_cmp_gt_u32_e32 vcc, s28, v248
	s_and_saveexec_b64 s[18:19], vcc
	s_cmp_eq_u32 s27, 0
	s_cbranch_scc1 .Ltr_m0_0_1
	s_cmp_eq_u32 s27, 2
	s_cbranch_scc1 .Ltr_m2_0_1
	v_add_u32_e32 v249, 0x800, v248
	v_cmp_gt_u32_e32 vcc, 0xc18, v248
	v_subrev_u32_e32 v226, 24, v248
	s_nop 1
	v_cndmask_b32_e32 v249, v226, v249, vcc
	v_cmp_gt_u32_e32 vcc, 0xc00, v248
	s_nop 1
	v_cndmask_b32_e32 v248, v249, v248, vcc
	s_branch .Ltr_m0_0_1

.Ltr_m0_0_1:
	v_mul_lo_u32 v248, v248, s26
	v_add_lshl_u32 v248, v248, v250, 1
	global_store_dwordx4 v248, v[236:239], s[24:25]
	s_or_b64 exec, exec, s[18:19]
	v_add_u32_e32 v248, 16, v212
	v_add_u32_e32 v248, s29, v248
	v_cmp_gt_u32_e32 vcc, s28, v248
	s_and_saveexec_b64 s[18:19], vcc
	s_cmp_eq_u32 s27, 0
	s_cbranch_scc1 .Ltr_m0_0_2
	s_cmp_eq_u32 s27, 2
	s_cbranch_scc1 .Ltr_m2_0_2
	v_add_u32_e32 v249, 0x800, v248
	v_cmp_gt_u32_e32 vcc, 0xc18, v248
	v_subrev_u32_e32 v226, 24, v248
	s_nop 1
	v_cndmask_b32_e32 v249, v226, v249, vcc
	v_cmp_gt_u32_e32 vcc, 0xc00, v248
	s_nop 1
	v_cndmask_b32_e32 v248, v249, v248, vcc
	s_branch .Ltr_m0_0_2

.Ltr_m0_0_2:
	v_mul_lo_u32 v248, v248, s26
	v_add_lshl_u32 v248, v248, v250, 1
	global_store_dwordx4 v248, v[240:243], s[24:25]
	s_or_b64 exec, exec, s[18:19]
	v_add_u32_e32 v248, 24, v212
	v_add_u32_e32 v248, s29, v248
	v_cmp_gt_u32_e32 vcc, s28, v248
	s_and_saveexec_b64 s[18:19], vcc
	s_cmp_eq_u32 s27, 0
	s_cbranch_scc1 .Ltr_m0_0_3
	s_cmp_eq_u32 s27, 2
	s_cbranch_scc1 .Ltr_m2_0_3
	v_add_u32_e32 v249, 0x800, v248
	v_cmp_gt_u32_e32 vcc, 0xc18, v248
	v_subrev_u32_e32 v226, 24, v248
	s_nop 1
	v_cndmask_b32_e32 v249, v226, v249, vcc
	v_cmp_gt_u32_e32 vcc, 0xc00, v248
	s_nop 1
	v_cndmask_b32_e32 v248, v249, v248, vcc
	s_branch .Ltr_m0_0_3

.Ltr_m0_0_3:
	v_mul_lo_u32 v248, v248, s26
	v_add_lshl_u32 v248, v248, v250, 1
	global_store_dwordx4 v248, v[244:247], s[24:25]
	s_or_b64 exec, exec, s[18:19]
	v_readlane_b32 s23, v230, 41
	v_readlane_b32 s24, v230, 8
	v_readlane_b32 s25, v230, 9
	v_readlane_b32 s26, v230, 10
	v_readlane_b32 s27, v230, 11
	v_readlane_b32 s28, v230, 12
	v_readlane_b32 s29, v230, 13
	v_readlane_b32 s30, v230, 14
	v_readlane_b32 s31, v230, 15
	s_cmp_eq_u32 s23, 0
	s_cbranch_scc1 .Ltr_done
	s_waitcnt vmcnt(36)
	s_cmp_eq_u32 s31, 0
	s_cbranch_scc1 .Ltr_ns1
	v_mul_f32_e32 v32, v32, v136
	v_mul_f32_e32 v36, v36, v137
	v_mul_f32_e32 v33, v33, v136
	v_mul_f32_e32 v37, v37, v137
	v_mul_f32_e32 v34, v34, v136
	v_mul_f32_e32 v38, v38, v137
	v_mul_f32_e32 v35, v35, v136
	v_mul_f32_e32 v39, v39, v137
	v_mul_f32_e32 v40, v40, v138
	v_mul_f32_e32 v44, v44, v139
	v_mul_f32_e32 v41, v41, v138
	v_mul_f32_e32 v45, v45, v139
	v_mul_f32_e32 v42, v42, v138
	v_mul_f32_e32 v46, v46, v139
	v_mul_f32_e32 v43, v43, v138
	v_mul_f32_e32 v47, v47, v139
	v_mul_f32_e32 v48, v48, v140
	v_mul_f32_e32 v52, v52, v141
	v_mul_f32_e32 v49, v49, v140
	v_mul_f32_e32 v53, v53, v141
	v_mul_f32_e32 v50, v50, v140
	v_mul_f32_e32 v54, v54, v141
	v_mul_f32_e32 v51, v51, v140
	v_mul_f32_e32 v55, v55, v141
	v_mul_f32_e32 v56, v56, v142
	v_mul_f32_e32 v60, v60, v143
	v_mul_f32_e32 v57, v57, v142
	v_mul_f32_e32 v61, v61, v143
	v_mul_f32_e32 v58, v58, v142
	v_mul_f32_e32 v62, v62, v143
	v_mul_f32_e32 v59, v59, v142
	v_mul_f32_e32 v63, v63, v143
.Ltr_ns1:
	v_cvt_pk_bf16_f32 v226, v32, v36
	v_cvt_pk_bf16_f32 v227, v33, v37
	v_cvt_pk_bf16_f32 v228, v34, v38
	v_cvt_pk_bf16_f32 v229, v35, v39
	ds_write_b32 v214, v226 offset:0
	ds_write_b32 v214, v227 offset:144
	ds_write_b32 v214, v228 offset:288
	ds_write_b32 v214, v229 offset:432
	v_cvt_pk_bf16_f32 v226, v40, v44
	v_cvt_pk_bf16_f32 v227, v41, v45
	v_cvt_pk_bf16_f32 v228, v42, v46
	v_cvt_pk_bf16_f32 v229, v43, v47
	ds_write_b32 v214, v226 offset:32
	ds_write_b32 v214, v227 offset:176
	ds_write_b32 v214, v228 offset:320
	ds_write_b32 v214, v229 offset:464
	v_cvt_pk_bf16_f32 v226, v48, v52
	v_cvt_pk_bf16_f32 v227, v49, v53
	v_cvt_pk_bf16_f32 v228, v50, v54
	v_cvt_pk_bf16_f32 v229, v51, v55
	ds_write_b32 v214, v226 offset:64
	ds_write_b32 v214, v227 offset:208
	ds_write_b32 v214, v228 offset:352
	ds_write_b32 v214, v229 offset:496
	v_cvt_pk_bf16_f32 v226, v56, v60
	v_cvt_pk_bf16_f32 v227, v57, v61
	v_cvt_pk_bf16_f32 v228, v58, v62
	v_cvt_pk_bf16_f32 v229, v59, v63
	ds_write_b32 v214, v226 offset:96
	ds_write_b32 v214, v227 offset:240
	ds_write_b32 v214, v228 offset:384
	ds_write_b32 v214, v229 offset:528
	s_waitcnt lgkmcnt(0)
	ds_read_b128 v[232:235], v215 offset:0
	ds_read_b128 v[236:239], v215 offset:1152
	ds_read_b128 v[240:243], v215 offset:2304
	ds_read_b128 v[244:247], v215 offset:3456
	v_lshl_add_u32 v250, v213, 3, s30
	s_waitcnt lgkmcnt(0)
	v_add_u32_e32 v248, 0, v212
	v_add_u32_e32 v248, s29, v248
	v_cmp_gt_u32_e32 vcc, s28, v248
	s_and_saveexec_b64 s[18:19], vcc
	s_cmp_eq_u32 s27, 0
	s_cbranch_scc1 .Ltr_m0_1_0
	s_cmp_eq_u32 s27, 2
	s_cbranch_scc1 .Ltr_m2_1_0
	v_add_u32_e32 v249, 0x800, v248
	v_cmp_gt_u32_e32 vcc, 0xc18, v248
	v_subrev_u32_e32 v226, 24, v248
	s_nop 1
	v_cndmask_b32_e32 v249, v226, v249, vcc
	v_cmp_gt_u32_e32 vcc, 0xc00, v248
	s_nop 1
	v_cndmask_b32_e32 v248, v249, v248, vcc
	s_branch .Ltr_m0_1_0

.Ltr_m0_1_3:
	v_mul_lo_u32 v248, v248, s26
	v_add_lshl_u32 v248, v248, v250, 1
	global_store_dwordx4 v248, v[244:247], s[24:25]
	s_or_b64 exec, exec, s[18:19]
	v_readlane_b32 s23, v230, 42
	v_readlane_b32 s24, v230, 16
	v_readlane_b32 s25, v230, 17
	v_readlane_b32 s26, v230, 18
	v_readlane_b32 s27, v230, 19
	v_readlane_b32 s28, v230, 20
	v_readlane_b32 s29, v230, 21
	v_readlane_b32 s30, v230, 22
	v_readlane_b32 s31, v230, 23
	s_cmp_eq_u32 s23, 0
	s_cbranch_scc1 .Ltr_done
	s_waitcnt vmcnt(24)
	s_cmp_eq_u32 s31, 0
	s_cbranch_scc1 .Ltr_ns2
	v_mul_f32_e32 v64, v64, v144
	v_mul_f32_e32 v68, v68, v145
	v_mul_f32_e32 v65, v65, v144
	v_mul_f32_e32 v69, v69, v145
	v_mul_f32_e32 v66, v66, v144
	v_mul_f32_e32 v70, v70, v145
	v_mul_f32_e32 v67, v67, v144
	v_mul_f32_e32 v71, v71, v145
	v_mul_f32_e32 v72, v72, v146
	v_mul_f32_e32 v76, v76, v147
	v_mul_f32_e32 v73, v73, v146
	v_mul_f32_e32 v77, v77, v147
	v_mul_f32_e32 v74, v74, v146
	v_mul_f32_e32 v78, v78, v147
	v_mul_f32_e32 v75, v75, v146
	v_mul_f32_e32 v79, v79, v147
	v_mul_f32_e32 v80, v80, v148
	v_mul_f32_e32 v84, v84, v149
	v_mul_f32_e32 v81, v81, v148
	v_mul_f32_e32 v85, v85, v149
	v_mul_f32_e32 v82, v82, v148
	v_mul_f32_e32 v86, v86, v149
	v_mul_f32_e32 v83, v83, v148
	v_mul_f32_e32 v87, v87, v149
	v_mul_f32_e32 v88, v88, v150
	v_mul_f32_e32 v92, v92, v151
	v_mul_f32_e32 v89, v89, v150
	v_mul_f32_e32 v93, v93, v151
	v_mul_f32_e32 v90, v90, v150
	v_mul_f32_e32 v94, v94, v151
	v_mul_f32_e32 v91, v91, v150
	v_mul_f32_e32 v95, v95, v151
.Ltr_ns2:
	v_cvt_pk_bf16_f32 v226, v64, v68
	v_cvt_pk_bf16_f32 v227, v65, v69
	v_cvt_pk_bf16_f32 v228, v66, v70
	v_cvt_pk_bf16_f32 v229, v67, v71
	ds_write_b32 v214, v226 offset:0
	ds_write_b32 v214, v227 offset:144
	ds_write_b32 v214, v228 offset:288
	ds_write_b32 v214, v229 offset:432
	v_cvt_pk_bf16_f32 v226, v72, v76
	v_cvt_pk_bf16_f32 v227, v73, v77
	v_cvt_pk_bf16_f32 v228, v74, v78
	v_cvt_pk_bf16_f32 v229, v75, v79
	ds_write_b32 v214, v226 offset:32
	ds_write_b32 v214, v227 offset:176
	ds_write_b32 v214, v228 offset:320
	ds_write_b32 v214, v229 offset:464
	v_cvt_pk_bf16_f32 v226, v80, v84
	v_cvt_pk_bf16_f32 v227, v81, v85
	v_cvt_pk_bf16_f32 v228, v82, v86
	v_cvt_pk_bf16_f32 v229, v83, v87
	ds_write_b32 v214, v226 offset:64
	ds_write_b32 v214, v227 offset:208
	ds_write_b32 v214, v228 offset:352
	ds_write_b32 v214, v229 offset:496
	v_cvt_pk_bf16_f32 v226, v88, v92
	v_cvt_pk_bf16_f32 v227, v89, v93
	v_cvt_pk_bf16_f32 v228, v90, v94
	v_cvt_pk_bf16_f32 v229, v91, v95
	ds_write_b32 v214, v226 offset:96
	ds_write_b32 v214, v227 offset:240
	ds_write_b32 v214, v228 offset:384
	ds_write_b32 v214, v229 offset:528
	s_waitcnt lgkmcnt(0)
	ds_read_b128 v[232:235], v215 offset:0
	ds_read_b128 v[236:239], v215 offset:1152
	ds_read_b128 v[240:243], v215 offset:2304
	ds_read_b128 v[244:247], v215 offset:3456
	v_lshl_add_u32 v250, v213, 3, s30
	s_waitcnt lgkmcnt(0)
	v_add_u32_e32 v248, 0, v212
	v_add_u32_e32 v248, s29, v248
	v_cmp_gt_u32_e32 vcc, s28, v248
	s_and_saveexec_b64 s[18:19], vcc
	s_cmp_eq_u32 s27, 0
	s_cbranch_scc1 .Ltr_m0_2_0
	s_cmp_eq_u32 s27, 2
	s_cbranch_scc1 .Ltr_m2_2_0
	v_add_u32_e32 v249, 0x800, v248
	v_cmp_gt_u32_e32 vcc, 0xc18, v248
	v_subrev_u32_e32 v226, 24, v248
	s_nop 1
	v_cndmask_b32_e32 v249, v226, v249, vcc
	v_cmp_gt_u32_e32 vcc, 0xc00, v248
	s_nop 1
	v_cndmask_b32_e32 v248, v249, v248, vcc
	s_branch .Ltr_m0_2_0

.Ltr_m0_2_3:
	v_mul_lo_u32 v248, v248, s26
	v_add_lshl_u32 v248, v248, v250, 1
	global_store_dwordx4 v248, v[244:247], s[24:25]
	s_or_b64 exec, exec, s[18:19]
	v_readlane_b32 s23, v230, 43
	v_readlane_b32 s24, v230, 24
	v_readlane_b32 s25, v230, 25
	v_readlane_b32 s26, v230, 26
	v_readlane_b32 s27, v230, 27
	v_readlane_b32 s28, v230, 28
	v_readlane_b32 s29, v230, 29
	v_readlane_b32 s30, v230, 30
	v_readlane_b32 s31, v230, 31
	s_cmp_eq_u32 s23, 0
	s_cbranch_scc1 .Ltr_done
	s_waitcnt vmcnt(12)
	s_cmp_eq_u32 s31, 0
	s_cbranch_scc1 .Ltr_ns3
	v_mul_f32_e32 v96, v96, v192
	v_mul_f32_e32 v100, v100, v193
	v_mul_f32_e32 v97, v97, v192
	v_mul_f32_e32 v101, v101, v193
	v_mul_f32_e32 v98, v98, v192
	v_mul_f32_e32 v102, v102, v193
	v_mul_f32_e32 v99, v99, v192
	v_mul_f32_e32 v103, v103, v193
	v_mul_f32_e32 v104, v104, v194
	v_mul_f32_e32 v108, v108, v195
	v_mul_f32_e32 v105, v105, v194
	v_mul_f32_e32 v109, v109, v195
	v_mul_f32_e32 v106, v106, v194
	v_mul_f32_e32 v110, v110, v195
	v_mul_f32_e32 v107, v107, v194
	v_mul_f32_e32 v111, v111, v195
	v_mul_f32_e32 v112, v112, v196
	v_mul_f32_e32 v116, v116, v197
	v_mul_f32_e32 v113, v113, v196
	v_mul_f32_e32 v117, v117, v197
	v_mul_f32_e32 v114, v114, v196
	v_mul_f32_e32 v118, v118, v197
	v_mul_f32_e32 v115, v115, v196
	v_mul_f32_e32 v119, v119, v197
	v_mul_f32_e32 v120, v120, v198
	v_mul_f32_e32 v124, v124, v199
	v_mul_f32_e32 v121, v121, v198
	v_mul_f32_e32 v125, v125, v199
	v_mul_f32_e32 v122, v122, v198
	v_mul_f32_e32 v126, v126, v199
	v_mul_f32_e32 v123, v123, v198
	v_mul_f32_e32 v127, v127, v199
.Ltr_ns3:
	v_cvt_pk_bf16_f32 v226, v96, v100
	v_cvt_pk_bf16_f32 v227, v97, v101
	v_cvt_pk_bf16_f32 v228, v98, v102
	v_cvt_pk_bf16_f32 v229, v99, v103
	ds_write_b32 v214, v226 offset:0
	ds_write_b32 v214, v227 offset:144
	ds_write_b32 v214, v228 offset:288
	ds_write_b32 v214, v229 offset:432
	v_cvt_pk_bf16_f32 v226, v104, v108
	v_cvt_pk_bf16_f32 v227, v105, v109
	v_cvt_pk_bf16_f32 v228, v106, v110
	v_cvt_pk_bf16_f32 v229, v107, v111
	ds_write_b32 v214, v226 offset:32
	ds_write_b32 v214, v227 offset:176
	ds_write_b32 v214, v228 offset:320
	ds_write_b32 v214, v229 offset:464
	v_cvt_pk_bf16_f32 v226, v112, v116
	v_cvt_pk_bf16_f32 v227, v113, v117
	v_cvt_pk_bf16_f32 v228, v114, v118
	v_cvt_pk_bf16_f32 v229, v115, v119
	ds_write_b32 v214, v226 offset:64
	ds_write_b32 v214, v227 offset:208
	ds_write_b32 v214, v228 offset:352
	ds_write_b32 v214, v229 offset:496
	v_cvt_pk_bf16_f32 v226, v120, v124
	v_cvt_pk_bf16_f32 v227, v121, v125
	v_cvt_pk_bf16_f32 v228, v122, v126
	v_cvt_pk_bf16_f32 v229, v123, v127
	ds_write_b32 v214, v226 offset:96
	ds_write_b32 v214, v227 offset:240
	ds_write_b32 v214, v228 offset:384
	ds_write_b32 v214, v229 offset:528
	s_waitcnt lgkmcnt(0)
	ds_read_b128 v[232:235], v215 offset:0
	ds_read_b128 v[236:239], v215 offset:1152
	ds_read_b128 v[240:243], v215 offset:2304
	ds_read_b128 v[244:247], v215 offset:3456
	v_lshl_add_u32 v250, v213, 3, s30
	s_waitcnt lgkmcnt(0)
	v_add_u32_e32 v248, 0, v212
	v_add_u32_e32 v248, s29, v248
	v_cmp_gt_u32_e32 vcc, s28, v248
	s_and_saveexec_b64 s[18:19], vcc
	s_cmp_eq_u32 s27, 0
	s_cbranch_scc1 .Ltr_m0_3_0
	s_cmp_eq_u32 s27, 2
	s_cbranch_scc1 .Ltr_m2_3_0
	v_add_u32_e32 v249, 0x800, v248
	v_cmp_gt_u32_e32 vcc, 0xc18, v248
	v_subrev_u32_e32 v226, 24, v248
	s_nop 1
	v_cndmask_b32_e32 v249, v226, v249, vcc
	v_cmp_gt_u32_e32 vcc, 0xc00, v248
	s_nop 1
	v_cndmask_b32_e32 v248, v249, v248, vcc
	s_branch .Ltr_m0_3_0

.Ltr_m0_3_3:
	v_mul_lo_u32 v248, v248, s26
	v_add_lshl_u32 v248, v248, v250, 1
	global_store_dwordx4 v248, v[244:247], s[24:25]
	s_or_b64 exec, exec, s[18:19]
	v_readlane_b32 s23, v230, 44
	v_readlane_b32 s24, v230, 32
	v_readlane_b32 s25, v230, 33
	v_readlane_b32 s26, v230, 34
	v_readlane_b32 s27, v230, 35
	v_readlane_b32 s28, v230, 36
	v_readlane_b32 s29, v230, 37
	v_readlane_b32 s30, v230, 38
	v_readlane_b32 s31, v230, 39
	s_cmp_eq_u32 s23, 0
	s_cbranch_scc1 .Ltr_done
	s_waitcnt vmcnt(0)
	s_cmp_eq_u32 s31, 0
	s_cbranch_scc1 .Ltr_ns4
	v_mul_f32_e32 v160, v160, v204
	v_mul_f32_e32 v164, v164, v205
	v_mul_f32_e32 v161, v161, v204
	v_mul_f32_e32 v165, v165, v205
	v_mul_f32_e32 v162, v162, v204
	v_mul_f32_e32 v166, v166, v205
	v_mul_f32_e32 v163, v163, v204
	v_mul_f32_e32 v167, v167, v205
	v_mul_f32_e32 v168, v168, v206
	v_mul_f32_e32 v172, v172, v207
	v_mul_f32_e32 v169, v169, v206
	v_mul_f32_e32 v173, v173, v207
	v_mul_f32_e32 v170, v170, v206
	v_mul_f32_e32 v174, v174, v207
	v_mul_f32_e32 v171, v171, v206
	v_mul_f32_e32 v175, v175, v207
	v_mul_f32_e32 v176, v176, v208
	v_mul_f32_e32 v180, v180, v209
	v_mul_f32_e32 v177, v177, v208
	v_mul_f32_e32 v181, v181, v209
	v_mul_f32_e32 v178, v178, v208
	v_mul_f32_e32 v182, v182, v209
	v_mul_f32_e32 v179, v179, v208
	v_mul_f32_e32 v183, v183, v209
	v_mul_f32_e32 v184, v184, v210
	v_mul_f32_e32 v188, v188, v211
	v_mul_f32_e32 v185, v185, v210
	v_mul_f32_e32 v189, v189, v211
	v_mul_f32_e32 v186, v186, v210
	v_mul_f32_e32 v190, v190, v211
	v_mul_f32_e32 v187, v187, v210
	v_mul_f32_e32 v191, v191, v211
.Ltr_ns4:
	v_cvt_pk_bf16_f32 v226, v160, v164
	v_cvt_pk_bf16_f32 v227, v161, v165
	v_cvt_pk_bf16_f32 v228, v162, v166
	v_cvt_pk_bf16_f32 v229, v163, v167
	ds_write_b32 v214, v226 offset:0
	ds_write_b32 v214, v227 offset:144
	ds_write_b32 v214, v228 offset:288
	ds_write_b32 v214, v229 offset:432
	v_cvt_pk_bf16_f32 v226, v168, v172
	v_cvt_pk_bf16_f32 v227, v169, v173
	v_cvt_pk_bf16_f32 v228, v170, v174
	v_cvt_pk_bf16_f32 v229, v171, v175
	ds_write_b32 v214, v226 offset:32
	ds_write_b32 v214, v227 offset:176
	ds_write_b32 v214, v228 offset:320
	ds_write_b32 v214, v229 offset:464
	v_cvt_pk_bf16_f32 v226, v176, v180
	v_cvt_pk_bf16_f32 v227, v177, v181
	v_cvt_pk_bf16_f32 v228, v178, v182
	v_cvt_pk_bf16_f32 v229, v179, v183
	ds_write_b32 v214, v226 offset:64
	ds_write_b32 v214, v227 offset:208
	ds_write_b32 v214, v228 offset:352
	ds_write_b32 v214, v229 offset:496
	v_cvt_pk_bf16_f32 v226, v184, v188
	v_cvt_pk_bf16_f32 v227, v185, v189
	v_cvt_pk_bf16_f32 v228, v186, v190
	v_cvt_pk_bf16_f32 v229, v187, v191
	ds_write_b32 v214, v226 offset:96
	ds_write_b32 v214, v227 offset:240
	ds_write_b32 v214, v228 offset:384
	ds_write_b32 v214, v229 offset:528
	s_waitcnt lgkmcnt(0)
	ds_read_b128 v[232:235], v215 offset:0
	ds_read_b128 v[236:239], v215 offset:1152
	ds_read_b128 v[240:243], v215 offset:2304
	ds_read_b128 v[244:247], v215 offset:3456
	v_lshl_add_u32 v250, v213, 3, s30
	s_waitcnt lgkmcnt(0)
	v_add_u32_e32 v248, 0, v212
	v_add_u32_e32 v248, s29, v248
	v_cmp_gt_u32_e32 vcc, s28, v248
	s_and_saveexec_b64 s[18:19], vcc
	s_cmp_eq_u32 s27, 0
	s_cbranch_scc1 .Ltr_m0_4_0
	s_cmp_eq_u32 s27, 2
	s_cbranch_scc1 .Ltr_m2_4_0
	v_add_u32_e32 v249, 0x800, v248
	v_cmp_gt_u32_e32 vcc, 0xc18, v248
	v_subrev_u32_e32 v226, 24, v248
	s_nop 1
	v_cndmask_b32_e32 v249, v226, v249, vcc
	v_cmp_gt_u32_e32 vcc, 0xc00, v248
	s_nop 1
	v_cndmask_b32_e32 v248, v249, v248, vcc
	s_branch .Ltr_m0_4_0

.Ltr_m0_4_3:
	v_mul_lo_u32 v248, v248, s26
	v_add_lshl_u32 v248, v248, v250, 1
	global_store_dwordx4 v248, v[244:247], s[24:25]
	s_or_b64 exec, exec, s[18:19]
.Ltr_done:
	s_waitcnt vmcnt(0)
	v_and_b32_e32 v16, 31, v153
	s_load_dwordx16 s[8:23], s[0:1], 0xc0
	s_waitcnt lgkmcnt(0)
